# sweep 2 far tiles: the 16 packed f32 FMAs interleaved with MFMAs split into scalar v_fma_f32 pairs (bit-identical)
# speedup vs baseline: 1.0038x; 1.0004x over previous
; #define SBAR() __builtin_amdgcn_sched_barrier(0)
; template <bool DIFF> ...
;     ...
;       BIAS_APPLY(t, 0, a0, b0, cb0);
;       { const float x1 = fmaf(cb0, C, e1), x2 = fmaf(cb0, C, e2);
; #pragma unroll
;       for (int r = 0; r < 16; ++r) a0[r] = __builtin_amdgcn_exp2f(fmaf(a0[r], C, x1));
;       if (DIFF) {
; #pragma unroll
;         for (int r = 0; r < 16; ++r) a0[r] = fmaf(nsg, __builtin_amdgcn_exp2f(fmaf(b0[r], C, x2)), a0[r]);
;       } }
;       PK4(a0, 0, pa0); PK4(a0, 8, pa1);
;       SBAR();
;       pv_step<0>(o, vb0, pa0); pv_step<1>(o, vb0, pa1);
.Lsw2f:
	ds_read_b128 v[64:67], v176
	ds_read_b128 v[68:71], v172 offset:36864
	ds_read_b128 v[72:75], v177
	ds_read_b128 v[76:79], v176 offset:8192
	s_waitcnt lgkmcnt(2)
	v_mfma_f32_32x32x16_bf16 v[112:127], v[64:67], v[68:71], 0
	ds_read_b128 v[64:67], v171 offset:36864
	ds_read_b128 v[128:131], v177 offset:8192
	s_waitcnt lgkmcnt(1)
	v_mfma_f32_32x32x16_bf16 v[96:111], v[72:75], v[64:67], 0
	ds_read_b128 v[72:75], v178
	ds_read_b128 v[132:135], v170 offset:36864
	ds_read_b128 v[80:83], v179
	ds_read_b128 v[136:139], v178 offset:8192
	ds_read_b128 v[140:143], v169 offset:36864
	ds_read_b128 v[192:195], v179 offset:8192
	s_waitcnt lgkmcnt(1)
	v_mfma_f32_32x32x16_bf16 v[96:111], v[80:83], v[140:143], v[96:111]
	v_mfma_f32_32x32x16_bf16 v[112:127], v[72:75], v[132:135], v[112:127]
	ds_read_b128 v[72:75], v180
	ds_read_b128 v[196:199], v168 offset:36864
	ds_read_b128 v[80:83], v181
	ds_read_b128 v[200:203], v180 offset:8192
	ds_read_b128 v[204:207], v167 offset:36864
	ds_read_b128 v[210:213], v181 offset:8192
	s_waitcnt lgkmcnt(1)
	v_mfma_f32_32x32x16_bf16 v[96:111], v[80:83], v[204:207], v[96:111]
	v_mfma_f32_32x32x16_bf16 v[112:127], v[72:75], v[196:199], v[112:127]
	ds_read_b128 v[72:75], v182
	ds_read_b128 v[214:217], v166 offset:36864
	ds_read_b128 v[80:83], v183
	ds_read_b128 v[218:221], v182 offset:8192
	ds_read_b128 v[222:225], v149 offset:36864
	ds_read_b128 v[226:229], v183 offset:8192
	s_waitcnt lgkmcnt(1)
	v_mfma_f32_32x32x16_bf16 v[96:111], v[80:83], v[222:225], v[96:111]
	v_mfma_f32_32x32x16_bf16 v[112:127], v[72:75], v[214:217], v[112:127]
	s_waitcnt lgkmcnt(0)
	v_mfma_f32_32x32x16_bf16 v[80:95], v[76:79], v[68:71], 0
	v_fmamk_f32 v235, v234, 0x3e38aa3b, v188
	v_fmamk_f32 v234, v234, 0x3e38aa3b, v187
	s_nop 8
	v_fmamk_f32 v112, v112, 0x3e38aa3b, v235
	v_fmamk_f32 v113, v113, 0x3e38aa3b, v235
	v_fmamk_f32 v114, v114, 0x3e38aa3b, v235
	v_fmamk_f32 v115, v115, 0x3e38aa3b, v235
	v_fmamk_f32 v116, v116, 0x3e38aa3b, v235
	v_fmamk_f32 v117, v117, 0x3e38aa3b, v235
	v_fmamk_f32 v96, v96, 0x3e38aa3b, v234
	v_fmamk_f32 v97, v97, 0x3e38aa3b, v234
	v_fmamk_f32 v98, v98, 0x3e38aa3b, v234
	v_fmamk_f32 v99, v99, 0x3e38aa3b, v234
	v_fmamk_f32 v100, v100, 0x3e38aa3b, v234
	v_fmamk_f32 v101, v101, 0x3e38aa3b, v234
	v_exp_f32_e32 v112, v112
	v_mfma_f32_32x32x16_bf16 v[64:79], v[128:131], v[64:67], 0
	v_exp_f32_e32 v113, v113
	v_exp_f32_e32 v114, v114
	v_exp_f32_e32 v115, v115
	v_exp_f32_e32 v116, v116
	v_exp_f32_e32 v117, v117
	v_fmamk_f32 v118, v118, 0x3e38aa3b, v235
	v_fmamk_f32 v119, v119, 0x3e38aa3b, v235
	v_fmamk_f32 v120, v120, 0x3e38aa3b, v235
	v_fmamk_f32 v121, v121, 0x3e38aa3b, v235
	v_fmamk_f32 v122, v122, 0x3e38aa3b, v235
	v_mfma_f32_32x32x16_bf16 v[80:95], v[136:139], v[132:135], v[80:95]
	v_fmamk_f32 v123, v123, 0x3e38aa3b, v235
	v_fmamk_f32 v124, v124, 0x3e38aa3b, v235
	v_fmamk_f32 v125, v125, 0x3e38aa3b, v235
	v_fmamk_f32 v126, v126, 0x3e38aa3b, v235
	v_fmac_f32_e32 v235, 0x3e38aa3b, v127
	v_exp_f32_e32 v96, v96
	v_exp_f32_e32 v97, v97
	v_exp_f32_e32 v98, v98
	v_exp_f32_e32 v99, v99
	v_exp_f32_e32 v100, v100
	v_exp_f32_e32 v101, v101
	v_mfma_f32_32x32x16_bf16 v[64:79], v[192:195], v[140:143], v[64:79]
	v_lshl_add_u64 v[128:129], v[150:151], 0, s[34:35]
	v_add_co_u32_e32 v130, vcc, s70, v128
	s_nop 1
	v_addc_co_u32_e32 v131, vcc, 0, v129, vcc
	v_add_co_u32_e32 v132, vcc, s71, v128
	v_lshl_add_u64 v[136:137], v[152:153], 0, s[34:35]
	s_nop 0
	v_addc_co_u32_e32 v133, vcc, 0, v129, vcc
	v_add_co_u32_e32 v138, vcc, s72, v136
	s_nop 1
	v_addc_co_u32_e32 v139, vcc, 0, v137, vcc
	v_add_co_u32_e32 v140, vcc, s73, v136
	global_load_dwordx4 v[128:131], v[130:131], off
	s_nop 0
	global_load_dwordx4 v[132:135], v[132:133], off
	v_addc_co_u32_e32 v141, vcc, 0, v137, vcc
	global_load_dwordx4 v[136:139], v[138:139], off
	s_nop 0
	global_load_dwordx4 v[140:143], v[140:141], off
	v_fmamk_f32 v102, v102, 0x3e38aa3b, v234
	v_fmamk_f32 v103, v103, 0x3e38aa3b, v234
	v_fmamk_f32 v104, v104, 0x3e38aa3b, v234
	v_fmamk_f32 v105, v105, 0x3e38aa3b, v234
	v_fmamk_f32 v106, v106, 0x3e38aa3b, v234
	v_fmamk_f32 v107, v107, 0x3e38aa3b, v234
	v_fmamk_f32 v108, v108, 0x3e38aa3b, v234
	v_fmamk_f32 v109, v109, 0x3e38aa3b, v234
	v_fmamk_f32 v110, v110, 0x3e38aa3b, v234
	v_fmac_f32_e32 v234, 0x3e38aa3b, v111
	v_exp_f32_e32 v118, v118
	v_exp_f32_e32 v119, v119
	v_exp_f32_e32 v120, v120
	v_mfma_f32_32x32x16_bf16 v[80:95], v[200:203], v[196:199], v[80:95]
	v_exp_f32_e32 v121, v121
	v_exp_f32_e32 v122, v122
	v_exp_f32_e32 v123, v123
	v_exp_f32_e32 v124, v124
	v_exp_f32_e32 v125, v125
	v_exp_f32_e32 v126, v126
	v_exp_f32_e32 v127, v235
	v_exp_f32_e32 v102, v102
	v_mfma_f32_32x32x16_bf16 v[64:79], v[210:213], v[204:207], v[64:79]
	v_exp_f32_e32 v103, v103
	v_exp_f32_e32 v104, v104
	v_exp_f32_e32 v105, v105
	v_exp_f32_e32 v106, v106
	v_exp_f32_e32 v107, v107
	v_exp_f32_e32 v108, v108
	v_exp_f32_e32 v109, v109
	v_exp_f32_e32 v110, v110
	v_mfma_f32_32x32x16_bf16 v[80:95], v[218:221], v[214:217], v[80:95]
	v_exp_f32_e32 v111, v234
	v_fma_f32 v96, v144, v96, v112
	v_fma_f32 v97, v145, v97, v113
	v_fma_f32 v98, v144, v98, v114
	v_fma_f32 v99, v145, v99, v115
	v_fma_f32 v100, v144, v100, v116
	v_fma_f32 v101, v145, v101, v117
	v_fma_f32 v102, v144, v102, v118
	v_fma_f32 v103, v145, v103, v119
	v_fma_f32 v104, v144, v104, v120
	v_fma_f32 v105, v145, v105, v121
	v_fma_f32 v106, v144, v106, v122
	v_fma_f32 v107, v145, v107, v123
	v_fma_f32 v108, v144, v108, v124
	v_fma_f32 v109, v145, v109, v125
	v_mfma_f32_32x32x16_bf16 v[64:79], v[226:229], v[222:225], v[64:79]
	v_fma_f32 v110, v144, v110, v126
	v_fma_f32 v111, v145, v111, v127
	v_cvt_pk_bf16_f32 v96, v96, v97
	v_cvt_pk_bf16_f32 v97, v98, v99
; #define SBAR() __builtin_amdgcn_sched_barrier(0)
; template <bool DIFF> ...
;     ...
;       pv_step<0>(o, vb0, pa0); pv_step<1>(o, vb0, pa1);
;       SBAR();
;       BIAS_APPLY(t, 1, a1, b1, cb1);
;       { const float x1 = fmaf(cb1, C, e1), x2 = fmaf(cb1, C, e2);
; #pragma unroll
;       for (int r = 0; r < 16; ++r) a1[r] = __builtin_amdgcn_exp2f(fmaf(a1[r], C, x1));
;       if (DIFF) {
; #pragma unroll
;         for (int r = 0; r < 16; ++r) a1[r] = fmaf(nsg, __builtin_amdgcn_exp2f(fmaf(b1[r], C, x2)), a1[r]);
;       } }
;       PK4(a1, 0, pa2); PK4(a1, 8, pa3);
;       SBAR();
;       pv_step<2>(o, vb0, pa2); pv_step<3>(o, vb0, pa3);
	v_cvt_pk_bf16_f32 v98, v100, v101
	v_cvt_pk_bf16_f32 v99, v102, v103
	s_nop 0
	v_permlane32_swap_b32_e32 v96, v98
	v_cvt_pk_bf16_f32 v100, v104, v105
	v_cvt_pk_bf16_f32 v101, v106, v107
	v_cvt_pk_bf16_f32 v102, v108, v109
	v_cvt_pk_bf16_f32 v103, v110, v111
	v_permlane32_swap_b32_e32 v97, v99
	v_permlane32_swap_b32_e32 v100, v102
	v_permlane32_swap_b32_e32 v101, v103
	ds_read_b64_tr_b16 v[104:105], v146 offset:0
	ds_read_b64_tr_b16 v[106:107], v146 offset:0x800
	ds_read_b64_tr_b16 v[108:109], v146 offset:0x200
	ds_read_b64_tr_b16 v[110:111], v146 offset:0xa00
	ds_read_b64_tr_b16 v[112:113], v146 offset:0x400
	ds_read_b64_tr_b16 v[114:115], v146 offset:0xc00
	ds_read_b64_tr_b16 v[116:117], v146 offset:0x600
	ds_read_b64_tr_b16 v[118:119], v146 offset:0xe00
	ds_read_b64_tr_b16 v[238:239], v146 offset:0x1000
	ds_read_b64_tr_b16 v[240:241], v146 offset:0x1800
	ds_read_b64_tr_b16 v[242:243], v146 offset:0x1200
	ds_read_b64_tr_b16 v[244:245], v146 offset:0x1a00
	ds_read_b64_tr_b16 v[246:247], v146 offset:0x1400
	ds_read_b64_tr_b16 v[248:249], v146 offset:0x1c00
	ds_read_b64_tr_b16 v[120:121], v146 offset:0x1600
	ds_read_b64_tr_b16 v[122:123], v146 offset:0x1e00
	v_fmamk_f32 v237, v236, 0x3e38aa3b, v188
	v_fmamk_f32 v236, v236, 0x3e38aa3b, v187
	v_fmamk_f32 v80, v80, 0x3e38aa3b, v237
	v_fmamk_f32 v81, v81, 0x3e38aa3b, v237
	v_fmamk_f32 v82, v82, 0x3e38aa3b, v237
	v_fmamk_f32 v83, v83, 0x3e38aa3b, v237
	v_fmamk_f32 v84, v84, 0x3e38aa3b, v237
	v_fmamk_f32 v85, v85, 0x3e38aa3b, v237
	v_fmamk_f32 v86, v86, 0x3e38aa3b, v237
	v_fmamk_f32 v87, v87, 0x3e38aa3b, v237
	s_waitcnt lgkmcnt(0)
	v_mfma_f32_32x32x16_bf16 v[0:15], v[96:99], v[104:107], v[0:15]
	v_fmamk_f32 v88, v88, 0x3e38aa3b, v237
	v_fmamk_f32 v89, v89, 0x3e38aa3b, v237
	v_fmamk_f32 v90, v90, 0x3e38aa3b, v237
	v_fmamk_f32 v91, v91, 0x3e38aa3b, v237
	v_fmamk_f32 v92, v92, 0x3e38aa3b, v237
	v_fmamk_f32 v93, v93, 0x3e38aa3b, v237
	v_fmamk_f32 v94, v94, 0x3e38aa3b, v237
	v_fmac_f32_e32 v237, 0x3e38aa3b, v95
	v_fmamk_f32 v64, v64, 0x3e38aa3b, v236
	v_fmamk_f32 v65, v65, 0x3e38aa3b, v236
	v_fmamk_f32 v66, v66, 0x3e38aa3b, v236
	v_fmamk_f32 v67, v67, 0x3e38aa3b, v236
	v_fmamk_f32 v68, v68, 0x3e38aa3b, v236
	v_fmamk_f32 v69, v69, 0x3e38aa3b, v236
	v_fmamk_f32 v70, v70, 0x3e38aa3b, v236
	v_mfma_f32_32x32x16_bf16 v[16:31], v[96:99], v[108:111], v[16:31]
	v_fmamk_f32 v71, v71, 0x3e38aa3b, v236
	v_fmamk_f32 v72, v72, 0x3e38aa3b, v236
	v_fmamk_f32 v73, v73, 0x3e38aa3b, v236
	v_fmamk_f32 v74, v74, 0x3e38aa3b, v236
	v_fmamk_f32 v75, v75, 0x3e38aa3b, v236
	v_fmamk_f32 v76, v76, 0x3e38aa3b, v236
	v_fmamk_f32 v77, v77, 0x3e38aa3b, v236
	v_fmamk_f32 v78, v78, 0x3e38aa3b, v236
	v_fmac_f32_e32 v236, 0x3e38aa3b, v79
	v_exp_f32_e32 v80, v80
	v_exp_f32_e32 v81, v81
	v_exp_f32_e32 v82, v82
	v_mfma_f32_32x32x16_bf16 v[32:47], v[96:99], v[112:115], v[32:47]
	v_exp_f32_e32 v83, v83
	v_exp_f32_e32 v84, v84
	v_exp_f32_e32 v85, v85
	v_exp_f32_e32 v86, v86
	v_exp_f32_e32 v87, v87
	v_exp_f32_e32 v88, v88
	v_exp_f32_e32 v89, v89
	v_mfma_f32_32x32x16_bf16 v[48:63], v[96:99], v[116:119], v[48:63]
	v_exp_f32_e32 v90, v90
	v_exp_f32_e32 v91, v91
	v_exp_f32_e32 v92, v92
	v_exp_f32_e32 v93, v93
	v_exp_f32_e32 v94, v94
	v_exp_f32_e32 v95, v237
	v_exp_f32_e32 v64, v64
	v_mfma_f32_32x32x16_bf16 v[0:15], v[100:103], v[238:241], v[0:15]
	v_exp_f32_e32 v65, v65
	v_exp_f32_e32 v66, v66
	v_exp_f32_e32 v67, v67
	v_exp_f32_e32 v68, v68
	v_exp_f32_e32 v69, v69
	v_exp_f32_e32 v70, v70
	v_exp_f32_e32 v71, v71
	v_mfma_f32_32x32x16_bf16 v[16:31], v[100:103], v[242:245], v[16:31]
	v_exp_f32_e32 v72, v72
	v_exp_f32_e32 v73, v73
	v_exp_f32_e32 v74, v74
	v_exp_f32_e32 v75, v75
	v_exp_f32_e32 v76, v76
	v_exp_f32_e32 v77, v77
	v_exp_f32_e32 v78, v78
	v_mfma_f32_32x32x16_bf16 v[32:47], v[100:103], v[246:249], v[32:47]
	v_exp_f32_e32 v79, v236
	v_fma_f32 v64, v144, v64, v80
	v_fma_f32 v65, v145, v65, v81
	v_fma_f32 v66, v144, v66, v82
	v_fma_f32 v67, v145, v67, v83
	v_fma_f32 v68, v144, v68, v84
	v_fma_f32 v69, v145, v69, v85
	v_fma_f32 v70, v144, v70, v86
	v_fma_f32 v71, v145, v71, v87
	v_fma_f32 v72, v144, v72, v88
	v_fma_f32 v73, v145, v73, v89
	v_fma_f32 v74, v144, v74, v90
	v_fma_f32 v75, v145, v75, v91
	v_mfma_f32_32x32x16_bf16 v[48:63], v[100:103], v[120:123], v[48:63]
	v_fma_f32 v76, v144, v76, v92
	v_fma_f32 v77, v145, v77, v93
	v_fma_f32 v78, v144, v78, v94
	v_fma_f32 v79, v145, v79, v95
	v_cvt_pk_bf16_f32 v64, v64, v65
	v_cvt_pk_bf16_f32 v65, v66, v67
	v_cvt_pk_bf16_f32 v66, v68, v69
	v_cvt_pk_bf16_f32 v67, v70, v71
	v_cvt_pk_bf16_f32 v68, v72, v73
	v_cvt_pk_bf16_f32 v69, v74, v75
	v_cvt_pk_bf16_f32 v70, v76, v77
	v_cvt_pk_bf16_f32 v71, v78, v79
	v_permlane32_swap_b32_e32 v64, v66
	v_permlane32_swap_b32_e32 v65, v67
	v_permlane32_swap_b32_e32 v68, v70
	v_permlane32_swap_b32_e32 v69, v71
	ds_read_b64_tr_b16 v[72:73], v146 offset:0x2000
	ds_read_b64_tr_b16 v[74:75], v146 offset:0x2800
	ds_read_b64_tr_b16 v[76:77], v146 offset:0x2200
	ds_read_b64_tr_b16 v[78:79], v146 offset:0x2a00
	ds_read_b64_tr_b16 v[80:81], v146 offset:0x2400
	ds_read_b64_tr_b16 v[82:83], v146 offset:0x2c00
	ds_read_b64_tr_b16 v[84:85], v146 offset:0x2600
	ds_read_b64_tr_b16 v[86:87], v146 offset:0x2e00
	ds_read_b64_tr_b16 v[238:239], v146 offset:0x3000
	ds_read_b64_tr_b16 v[240:241], v146 offset:0x3800
	ds_read_b64_tr_b16 v[242:243], v146 offset:0x3200
	ds_read_b64_tr_b16 v[244:245], v146 offset:0x3a00
	ds_read_b64_tr_b16 v[246:247], v146 offset:0x3400
	ds_read_b64_tr_b16 v[248:249], v146 offset:0x3c00
	ds_read_b64_tr_b16 v[88:89], v146 offset:0x3600
	ds_read_b64_tr_b16 v[90:91], v146 offset:0x3e00
	s_waitcnt lgkmcnt(8)
	v_mfma_f32_32x32x16_bf16 v[0:15], v[64:67], v[72:75], v[0:15]
	v_mfma_f32_32x32x16_bf16 v[16:31], v[64:67], v[76:79], v[16:31]
	v_mfma_f32_32x32x16_bf16 v[32:47], v[64:67], v[80:83], v[32:47]
	v_mfma_f32_32x32x16_bf16 v[48:63], v[64:67], v[84:87], v[48:63]
	s_waitcnt lgkmcnt(0)
	v_mfma_f32_32x32x16_bf16 v[0:15], v[68:71], v[238:241], v[0:15]
	s_add_u32 s34, s34, 0x20000
	s_addc_u32 s35, s35, 0
	v_add_u32_e32 v173, 64, v173
	s_add_i32 s93, s93, 64
	s_cmp_eq_u32 s2, s34
	v_mfma_f32_32x32x16_bf16 v[16:31], v[68:71], v[242:245], v[16:31]
	v_mfma_f32_32x32x16_bf16 v[32:47], v[68:71], v[246:249], v[32:47]
	v_mfma_f32_32x32x16_bf16 v[48:63], v[68:71], v[88:91], v[48:63]
	s_cbranch_scc1 .LBB0_326
	s_branch .LBB0_310
